# static s_setprio 1 for waves 4..7 for the whole kernel, per-segment flips removed in the GEMM loops
# speedup vs baseline: 1.0005x; 1.0005x over previous
; #define LAS __attribute__((address_space(3)))
; __global__ void __launch_bounds__(512, 2) mk_fwd(Args args) {
;     ...
;     const int tid = threadIdx.x, lane = tid & 63, wave = __builtin_amdgcn_readfirstlane(tid >> 6);
;     const int G = gridDim.x, bx = blockIdx.x;
;     const int vcu = (G % 8 == 0) ? (bx % 8) * (G / 8) + bx / 8 : bx;
;     const int gw = vcu * 8 + wave, ngw = G * 8;
;     unsigned char* ws = args.ws;
;     if (tid < 64) MISC[tid] = 0u;
;     __syncthreads();
;     XcdBarrier bar; bar.bar = (unsigned*)(ws + WS_CTL) + 4096; bar.x = 0; bar.st = MISC + 8;
;     if (!MK_MULTI) bar = xcd_barrier_post((unsigned*)(ws + WS_CTL) + 4096, MISC + 8);
;     const int lo = args.ph_lo, hi = args.ph_hi;
;     ...
;     if (IN(0)) for (int rr = 0; rr < DUP_PRO; ++rr) {
;         LAS float* scr = (LAS float*)(lds + wave * 16384);
;         for (int t = gw; t < DEPTH * 60 * 16; t += ngw) {
;             const int lr = t / (60 * 16), l = DEPTH - 1 - lr, r_ = t - lr * (60 * 16), strip = r_ >> 4, kb = r_ & 15;
;             const bool up = strip >= 28; const int c0 = (up ? strip - 28 : strip) * 256 + 4 * lane, pitch = up ? DFF : INC;
;             const float* wp = (up ? args.in[I_WUP] + (size_t)l * DM * DFF : args.in[I_WIN] + (size_t)l * DM * INC + C_I8) + (size_t)(kb * 128) * pitch + c0;
;             const float* gp = (up ? args.in[I_GMLPPRE] : args.in[I_GMIXPRE]) + l * DM + kb * 128;
;             f32x4 m = (f32x4){0.f, 0.f, 0.f, 0.f};
; #pragma unroll 16
;             for (int k = 0; k < 128; ++k) { const f32x4 v = *(const f32x4*)(wp + (size_t)k * pitch); const float g_ = __builtin_fabsf(gp[k]);
.LBB0_7:
	s_or_b64 exec, exec, s[4:5]
	s_load_dwordx2 s[46:47], s[88:89], 0x100
	v_readlane_b32 s2, v249, 2
	s_lshr_b32 s80, s82, 6
	s_cmp_ge_u32 s80, 4
	s_cbranch_scc0 .Lprio_older
	s_setprio 1
.Lprio_older:
	s_lshl_b32 s2, s2, 3
	s_lshl_b32 s92, s85, 3
	s_add_i32 s90, s2, s80
	v_writelane_b32 v249, s2, 7
	s_waitcnt lgkmcnt(0)
	s_cmp_lt_i32 s46, 1
	s_cselect_b64 s[2:3], -1, 0
	s_cmp_gt_i32 s47, 0
	v_writelane_b32 v249, s97, 8
	s_cselect_b64 s[4:5], -1, 0
	v_writelane_b32 v249, s85, 9
	s_and_b64 s[10:11], s[2:3], s[4:5]
	v_writelane_b32 v249, s46, 10
	s_andn2_b64 vcc, exec, s[10:11]
	v_and_b32_e32 v1, 63, v0
	v_writelane_b32 v249, s47, 11
	s_cbranch_vccnz .LBB0_215
	s_load_dwordx2 s[34:35], s[88:89], 0xe0
	s_load_dwordx2 s[36:37], s[88:89], 0xf8
	s_load_dwordx4 s[16:19], s[88:89], 0xd0
	s_load_dwordx2 s[38:39], s[88:89], 0xc0
	s_load_dwordx4 s[12:15], s[88:89], 0x0
	s_load_dwordx2 s[78:79], s[88:89], 0x10
	s_load_dwordx4 s[20:23], s[88:89], 0xa8
	s_load_dwordx4 s[24:27], s[88:89], 0x40
	s_cmpk_gt_i32 s90, 0xeff
	v_lshlrev_b32_e32 v6, 2, v1
	s_cbranch_scc1 .LBB0_17
	s_load_dwordx2 s[2:3], s[88:89], 0xf8
	v_readlane_b32 s4, v249, 2
	s_movk_i32 s46, 0x2000
	v_mov_b32_e32 v7, 0
	s_mov_b32 s47, s90
	s_waitcnt lgkmcnt(0)
	s_add_u32 s2, s2, 0x110000
	s_addc_u32 s3, s3, 0
	s_lshl_b32 s4, s4, 10
	s_lshl_b32 s5, s80, 7
	s_add_i32 s29, s4, s5
	s_lshl_b32 s33, s85, 10
	s_mov_b32 s5, 0
